# HG scan: recurrence rewritten on T = S - v_next with f = 1-k staged in LDS (one pk_fma per state pair instead of pk_add + pk_fma); per-token q row sums staged for the output correction
# speedup vs baseline: 1.0097x; 1.0040x over previous
; DI int TID() { int t = threadIdx.x; asm volatile("" : "+v"(t)); return t; }
; DI int BID() { int t = blockIdx.x; asm volatile("" : "+s"(t)); return t; }
; DI void phase_hg_scan(const Params& p, char* smem) {
;   const int tid = TID(), lane = tid & 63, wv = tid >> 6;
;   const int dpart = lane & 15, esub = lane >> 4, el = wv * 4 + esub;
;   const bf16_t* qb = (const bf16_t*)(p.ws + HG_Q);
;   const bf16_t* ib = (const bf16_t*)(p.ws + HG_I);
;   const int ltok = tid >> 4, ldc = tid & 15;
;   const int vtok = (tid & 127) >> 2, vec = tid & 3;
;   for (int item = BID(); item < 256; item += gridDim.x) {
;     const int b = item >> 6, h = (item >> 3) & 7, dir = (item >> 2) & 1, eq = item & 3;
;     const bf16_t* kk = (const bf16_t*)(p.ws + (dir ? HG_KB : HG_KF));
;     bf16_t* oo = (bf16_t*)(p.ws + (dir ? HG_OB : OFF_ABUF));
;     const size_t rowbase = (size_t)b * PL;
;     const int colq = h * 128 + ldc * 8, colv = h * 128 + eq * 32 + vec * 8, colo = h * 128 + eq * 32 + el;
;     auto posf = [&](int tau) { return dir ? (tau < CTXL ? CTXL - 1 - tau : PL - 1 - (tau - CTXL)) : tau; };
;     f32x2_t S[4];
; #pragma unroll
;     for (int j = 0; j < 4; ++j) S[j] = f32x2_t{0.f, 0.f};
;     uint4 aq, ak, av, bq, bk, bv;
;     av = make_uint4(0, 0, 0, 0); bv = av;
.LBB0_190:
	s_cmp_eq_u32 s12, 1
	s_mov_b64 s[0:1], -1
	s_cbranch_scc0 .LBB0_251
	v_writelane_b32 v255, s52, 6
	s_waitcnt vmcnt(1)
	v_mov_b32_e32 v0, v167
	s_mov_b32 s96, s50
	v_writelane_b32 v255, s53, 7
	v_writelane_b32 v255, s50, 8
	s_cmpk_gt_i32 s96, 0xff
	s_cbranch_scc1 .LBB0_250
	v_lshlrev_b32_e32 v2, 3, v0
	s_movk_i32 s0, 0x80
	v_lshrrev_b32_e32 v1, 4, v0
	v_ashrrev_i32_e32 v58, 4, v0
	v_and_b32_e32 v61, 0x78, v2
	v_cmp_gt_i32_e64 s[38:39], s0, v0
	s_movk_i32 s0, 0x7f
	v_and_b32_e32 v57, 15, v0
	v_bfi_b32 v59, -4, v58, v1
	v_lshrrev_b32_e32 v1, 2, v0
	v_bfe_u32 v60, v0, 2, 5
	v_and_b32_e32 v62, 24, v2
	v_cmp_lt_i32_e64 s[0:1], s0, v0
	v_lshlrev_b32_e32 v0, 9, v58
	v_lshlrev_b32_e32 v2, 1, v61
	v_writelane_b32 v255, s0, 9
	v_add3_u32 v64, 0, v0, v2
	v_lshlrev_b32_e32 v2, 2, v62
	v_writelane_b32 v255, s1, 10
	s_movk_i32 s3, 0xff
	v_lshlrev_b32_e32 v0, 7, v60
	v_add_u32_e32 v3, 0, v2
	s_movk_i32 s1, 0xdf
	s_add_i32 s0, 0, 0x11000
	v_bitop3_b32 v63, v1, s3, 31 bitop3:0x6c
	v_add_u32_e32 v65, v3, v0
	v_bitop3_b32 v68, v1, s1, 31 bitop3:0x6c
	v_add_u32_e32 v1, s0, v2
	v_cmp_lt_i32_e32 vcc, s3, v58
	v_mov_b32_e32 v2, 0xff
	v_mov_b32_e32 v3, 0x21ff
	v_cndmask_b32_e32 v2, v2, v3, vcc
	v_sub_u32_e32 v70, v2, v58
	v_cmp_lt_i32_e32 vcc, s1, v58
	v_mov_b32_e32 v2, 0xdf
	v_mov_b32_e32 v3, 0x21df
	v_cndmask_b32_e32 v2, v2, v3, vcc
	v_writelane_b32 v255, s74, 11
	v_add_u32_e32 v66, 32, v58
	v_or_b32_e32 v67, 32, v60
	v_lshl_add_u32 v69, v57, 4, 0
	v_add_u32_e32 v142, 1, v57
	v_lshlrev_b32_e32 v142, 7, v142
	v_lshlrev_b32_e32 v143, 2, v57
	v_add_u32_e32 v143, 0x12000, v143
	v_lshlrev_b32_e32 v164, 2, v58
	v_add_u32_e32 v164, 0x12000, v164
	v_sub_u32_e32 v71, v2, v58
	v_and_b32_e32 v110, 2, v57
	v_cmp_eq_u32_e64 s[42:43], 0, v110
	v_and_b32_e32 v111, 1, v57
	v_cmp_eq_u32_e64 s[44:45], 0, v111
	v_cmp_eq_u32_e64 s[46:47], 2, v57
	v_cmp_eq_u32_e64 s[48:49], 3, v57
	v_cmp_eq_u32_e64 s[50:51], 4, v57
	v_cmp_eq_u32_e64 s[52:53], 5, v57
	v_cmp_eq_u32_e64 s[54:55], 6, v57
	v_cmp_eq_u32_e64 s[56:57], 7, v57
	v_cmp_eq_u32_e64 s[58:59], 8, v57
	v_cmp_eq_u32_e64 s[60:61], 9, v57
	v_cmp_eq_u32_e64 s[62:63], 10, v57
	v_cmp_eq_u32_e64 s[64:65], 11, v57
	v_cmp_eq_u32_e64 s[66:67], 12, v57
	v_cmp_eq_u32_e64 s[68:69], 13, v57
	v_cmp_eq_u32_e64 s[70:71], 14, v57
	v_cmp_eq_u32_e64 s[72:73], 15, v57
	v_lshl_add_u32 v72, v59, 2, 0
	v_add_u32_e32 v73, v1, v0
	v_writelane_b32 v255, s75, 12
	s_branch .LBB0_194

.LBB0_196:
	s_or_b64 exec, exec, s[30:31]
	s_waitcnt vmcnt(1)
	v_lshlrev_b32_e32 v16, 16, v9
	v_lshlrev_b32_e32 v14, 16, v8
	v_lshlrev_b32_e32 v20, 16, v11
	v_lshlrev_b32_e32 v18, 16, v10
	v_and_b32_e32 v17, 0xffff0000, v9
	v_and_b32_e32 v15, 0xffff0000, v8
	v_and_b32_e32 v21, 0xffff0000, v11
	v_and_b32_e32 v19, 0xffff0000, v10
	ds_write_b128 v64, v[18:21] offset:256
	ds_write_b128 v64, v[14:17]
	v_add_f32_e32 v165, v18, v19
	v_add_f32_e32 v165, v165, v20
	v_add_f32_e32 v165, v165, v21
	v_add_f32_e32 v165, v165, v14
	v_add_f32_e32 v165, v165, v15
	v_add_f32_e32 v165, v165, v16
	v_add_f32_e32 v165, v165, v17
	s_nop 1
	v_add_f32_dpp v165, v165, v165 quad_perm:[1,0,3,2] row_mask:0xf bank_mask:0xf bound_ctrl:1
	s_nop 1
	v_add_f32_dpp v165, v165, v165 quad_perm:[2,3,0,1] row_mask:0xf bank_mask:0xf bound_ctrl:1
	s_nop 1
	v_add_f32_dpp v165, v165, v165 row_half_mirror row_mask:0xf bank_mask:0xf bound_ctrl:1
	s_nop 1
	v_add_f32_dpp v165, v165, v165 row_mirror row_mask:0xf bank_mask:0xf bound_ctrl:1
	ds_write_b32 v164, v165
	s_waitcnt vmcnt(0)
	v_lshlrev_b32_e32 v16, 16, v7
	v_lshlrev_b32_e32 v14, 16, v6
	v_and_b32_e32 v17, 0xffff0000, v7
	v_and_b32_e32 v15, 0xffff0000, v6
	v_lshlrev_b32_e32 v10, 16, v5
	v_lshlrev_b32_e32 v8, 16, v4
	v_and_b32_e32 v11, 0xffff0000, v5
	v_and_b32_e32 v9, 0xffff0000, v4
	v_sub_f32_e32 v14, 1.0, v14
	v_sub_f32_e32 v15, 1.0, v15
	v_sub_f32_e32 v16, 1.0, v16
	v_sub_f32_e32 v17, 1.0, v17
	ds_write_b128 v64, v[14:17] offset:16640
	v_sub_f32_e32 v8, 1.0, v8
	v_sub_f32_e32 v9, 1.0, v9
	v_sub_f32_e32 v10, 1.0, v10
	v_sub_f32_e32 v11, 1.0, v11
	ds_write_b128 v64, v[8:11] offset:16384
	s_and_saveexec_b64 s[30:31], s[38:39]
	s_cbranch_execz .LBB0_198
	v_lshlrev_b32_e32 v4, 16, v0
	v_and_b32_e32 v5, 0xffff0000, v0
	v_lshlrev_b32_e32 v6, 16, v1
	v_and_b32_e32 v7, 0xffff0000, v1
	v_lshlrev_b32_e32 v8, 16, v2
	v_and_b32_e32 v9, 0xffff0000, v2
	v_lshlrev_b32_e32 v10, 16, v3
	v_and_b32_e32 v11, 0xffff0000, v3
	ds_write_b128 v65, v[4:7] offset:32768
	ds_write_b128 v65, v[8:11] offset:32784

.LBB0_219:
	v_lshl_add_u32 v188, s25, 9, v69
	v_lshl_add_u32 v189, s25, 7, v72
	v_add_u32_e32 v190, 0x8400, v189
	v_add_u32_e32 v189, 0x8000, v189
	v_add_u32_e32 v160, v189, v142
	v_lshl_add_u32 v161, s25, 2, v143
	ds_read2_b32 v[172:173], v189 offset1:32
	ds_read2_b32 v[174:175], v189 offset0:64 offset1:96
	ds_read2_b32 v[176:177], v189 offset0:128 offset1:160
	ds_read2_b32 v[178:179], v189 offset0:192 offset1:224
	ds_read2_b32 v[180:181], v190 offset1:32
	ds_read2_b32 v[182:183], v190 offset0:64 offset1:96
	ds_read2_b32 v[184:185], v190 offset0:128 offset1:160
	ds_read2_b32 v[186:187], v190 offset0:192 offset1:224
	ds_read_b32 v160, v160
	ds_read_b32 v161, v161
	ds_read_b128 v[120:123], v188 offset:16384
	ds_read_b128 v[124:127], v188 offset:16640
	ds_read_b128 v[112:115], v188 offset:0
	ds_read_b128 v[116:119], v188 offset:256
	ds_read_b128 v[136:139], v188 offset:16896
	ds_read_b128 v[144:147], v188 offset:17152
	ds_read_b128 v[156:159], v188 offset:17408
	ds_read_b128 v[168:171], v188 offset:17664
	ds_read_b128 v[128:131], v188 offset:512
	ds_read_b128 v[132:135], v188 offset:768
	s_waitcnt lgkmcnt(8)
	v_pk_add_f32 v[36:37], v[36:37], v[172:173] op_sel_hi:[1,0] neg_lo:[0,1] neg_hi:[0,1]
	v_pk_add_f32 v[48:49], v[48:49], v[172:173] op_sel_hi:[1,0] neg_lo:[0,1] neg_hi:[0,1]
	v_pk_add_f32 v[38:39], v[38:39], v[172:173] op_sel_hi:[1,0] neg_lo:[0,1] neg_hi:[0,1]
	v_pk_add_f32 v[32:33], v[32:33], v[172:173] op_sel_hi:[1,0] neg_lo:[0,1] neg_hi:[0,1]
	v_sub_f32_e32 v172, v172, v173
	v_sub_f32_e32 v173, v173, v174
	v_sub_f32_e32 v174, v174, v175
	v_sub_f32_e32 v175, v175, v176
	v_sub_f32_e32 v176, v176, v177
	v_sub_f32_e32 v177, v177, v178
	v_sub_f32_e32 v178, v178, v179
	v_sub_f32_e32 v179, v179, v180
	v_sub_f32_e32 v180, v180, v181
	v_sub_f32_e32 v181, v181, v182
	v_sub_f32_e32 v182, v182, v183
	v_sub_f32_e32 v183, v183, v184
	v_sub_f32_e32 v184, v184, v185
	v_sub_f32_e32 v185, v185, v186
	v_sub_f32_e32 v186, v186, v187
	v_pk_fma_f32 v[244:245], v[120:121], v[36:37], v[172:173] op_sel_hi:[1,1,0]
	v_pk_fma_f32 v[246:247], v[122:123], v[48:49], v[172:173] op_sel_hi:[1,1,0]
	v_pk_fma_f32 v[248:249], v[124:125], v[38:39], v[172:173] op_sel_hi:[1,1,0]
	v_pk_fma_f32 v[250:251], v[126:127], v[32:33], v[172:173] op_sel_hi:[1,1,0]
	ds_read_b128 v[120:123], v188 offset:17920
	ds_read_b128 v[124:127], v188 offset:18176
	ds_read_b128 v[148:151], v188 offset:1024
	ds_read_b128 v[152:155], v188 offset:1280
	s_waitcnt lgkmcnt(8)
	v_pk_fma_f32 v[36:37], v[136:137], v[244:245], v[172:173] op_sel:[0,0,1] op_sel_hi:[1,1,1]
	v_pk_mul_f32 v[238:239], v[114:115], v[246:247]
	v_pk_fma_f32 v[48:49], v[138:139], v[246:247], v[172:173] op_sel:[0,0,1] op_sel_hi:[1,1,1]
	v_pk_fma_f32 v[238:239], v[112:113], v[244:245], v[238:239]
	v_pk_fma_f32 v[38:39], v[144:145], v[248:249], v[172:173] op_sel:[0,0,1] op_sel_hi:[1,1,1]
	v_pk_fma_f32 v[238:239], v[116:117], v[248:249], v[238:239]
	v_pk_fma_f32 v[32:33], v[146:147], v[250:251], v[172:173] op_sel:[0,0,1] op_sel_hi:[1,1,1]
	v_pk_fma_f32 v[238:239], v[118:119], v[250:251], v[238:239]
	ds_read_b128 v[136:139], v188 offset:18432
	ds_read_b128 v[144:147], v188 offset:18688
	ds_read_b128 v[112:115], v188 offset:1536
	ds_read_b128 v[116:119], v188 offset:1792
	s_waitcnt lgkmcnt(8)
	v_add_f32_e32 v214, v238, v239
	v_pk_fma_f32 v[244:245], v[156:157], v[36:37], v[174:175] op_sel_hi:[1,1,0]
	v_pk_mul_f32 v[240:241], v[130:131], v[48:49]
	v_pk_fma_f32 v[246:247], v[158:159], v[48:49], v[174:175] op_sel_hi:[1,1,0]
	v_pk_fma_f32 v[240:241], v[128:129], v[36:37], v[240:241]
	v_pk_fma_f32 v[248:249], v[168:169], v[38:39], v[174:175] op_sel_hi:[1,1,0]
	v_pk_fma_f32 v[240:241], v[132:133], v[38:39], v[240:241]
	v_pk_fma_f32 v[250:251], v[170:171], v[32:33], v[174:175] op_sel_hi:[1,1,0]
	v_pk_fma_f32 v[240:241], v[134:135], v[32:33], v[240:241]
	ds_read_b128 v[156:159], v188 offset:18944
	ds_read_b128 v[168:171], v188 offset:19200
	ds_read_b128 v[128:131], v188 offset:2048
	ds_read_b128 v[132:135], v188 offset:2304
	s_waitcnt lgkmcnt(8)
	v_add_f32_e32 v215, v240, v241
	v_pk_fma_f32 v[36:37], v[120:121], v[244:245], v[174:175] op_sel:[0,0,1] op_sel_hi:[1,1,1]
	v_pk_mul_f32 v[238:239], v[150:151], v[246:247]
	v_pk_fma_f32 v[48:49], v[122:123], v[246:247], v[174:175] op_sel:[0,0,1] op_sel_hi:[1,1,1]
	v_pk_fma_f32 v[238:239], v[148:149], v[244:245], v[238:239]
	v_pk_fma_f32 v[38:39], v[124:125], v[248:249], v[174:175] op_sel:[0,0,1] op_sel_hi:[1,1,1]
	v_pk_fma_f32 v[238:239], v[152:153], v[248:249], v[238:239]
	v_pk_fma_f32 v[32:33], v[126:127], v[250:251], v[174:175] op_sel:[0,0,1] op_sel_hi:[1,1,1]
	v_pk_fma_f32 v[238:239], v[154:155], v[250:251], v[238:239]
	ds_read_b128 v[120:123], v188 offset:19456
	ds_read_b128 v[124:127], v188 offset:19712
	ds_read_b128 v[148:151], v188 offset:2560
	ds_read_b128 v[152:155], v188 offset:2816
	s_waitcnt lgkmcnt(8)
	v_add_f32_e32 v216, v238, v239
	v_pk_fma_f32 v[244:245], v[136:137], v[36:37], v[176:177] op_sel_hi:[1,1,0]
	v_pk_mul_f32 v[240:241], v[114:115], v[48:49]
	v_pk_fma_f32 v[246:247], v[138:139], v[48:49], v[176:177] op_sel_hi:[1,1,0]
	v_pk_fma_f32 v[240:241], v[112:113], v[36:37], v[240:241]
	v_pk_fma_f32 v[248:249], v[144:145], v[38:39], v[176:177] op_sel_hi:[1,1,0]
	v_pk_fma_f32 v[240:241], v[116:117], v[38:39], v[240:241]
	v_pk_fma_f32 v[250:251], v[146:147], v[32:33], v[176:177] op_sel_hi:[1,1,0]
	v_pk_fma_f32 v[240:241], v[118:119], v[32:33], v[240:241]
	ds_read_b128 v[136:139], v188 offset:19968
	ds_read_b128 v[144:147], v188 offset:20224
	ds_read_b128 v[112:115], v188 offset:3072
	ds_read_b128 v[116:119], v188 offset:3328
	s_waitcnt lgkmcnt(8)
	v_add_f32_e32 v217, v240, v241
	v_pk_fma_f32 v[36:37], v[156:157], v[244:245], v[176:177] op_sel:[0,0,1] op_sel_hi:[1,1,1]
	v_pk_mul_f32 v[238:239], v[130:131], v[246:247]
	v_pk_fma_f32 v[48:49], v[158:159], v[246:247], v[176:177] op_sel:[0,0,1] op_sel_hi:[1,1,1]
	v_pk_fma_f32 v[238:239], v[128:129], v[244:245], v[238:239]
	v_pk_fma_f32 v[38:39], v[168:169], v[248:249], v[176:177] op_sel:[0,0,1] op_sel_hi:[1,1,1]
	v_pk_fma_f32 v[238:239], v[132:133], v[248:249], v[238:239]
	v_pk_fma_f32 v[32:33], v[170:171], v[250:251], v[176:177] op_sel:[0,0,1] op_sel_hi:[1,1,1]
	v_pk_fma_f32 v[238:239], v[134:135], v[250:251], v[238:239]
	ds_read_b128 v[156:159], v188 offset:20480
	ds_read_b128 v[168:171], v188 offset:20736
	ds_read_b128 v[128:131], v188 offset:3584
	ds_read_b128 v[132:135], v188 offset:3840
	s_waitcnt lgkmcnt(8)
	v_add_f32_e32 v218, v238, v239
	v_pk_fma_f32 v[244:245], v[120:121], v[36:37], v[178:179] op_sel_hi:[1,1,0]
	v_pk_mul_f32 v[240:241], v[150:151], v[48:49]
	v_pk_fma_f32 v[246:247], v[122:123], v[48:49], v[178:179] op_sel_hi:[1,1,0]
	v_pk_fma_f32 v[240:241], v[148:149], v[36:37], v[240:241]
	v_pk_fma_f32 v[248:249], v[124:125], v[38:39], v[178:179] op_sel_hi:[1,1,0]
	v_pk_fma_f32 v[240:241], v[152:153], v[38:39], v[240:241]
	v_pk_fma_f32 v[250:251], v[126:127], v[32:33], v[178:179] op_sel_hi:[1,1,0]
	v_pk_fma_f32 v[240:241], v[154:155], v[32:33], v[240:241]
	ds_read_b128 v[120:123], v188 offset:20992
	ds_read_b128 v[124:127], v188 offset:21248
	ds_read_b128 v[148:151], v188 offset:4096
	ds_read_b128 v[152:155], v188 offset:4352
	s_waitcnt lgkmcnt(8)
	v_add_f32_e32 v219, v240, v241
	v_pk_fma_f32 v[36:37], v[136:137], v[244:245], v[178:179] op_sel:[0,0,1] op_sel_hi:[1,1,1]
	v_pk_mul_f32 v[238:239], v[114:115], v[246:247]
	v_pk_fma_f32 v[48:49], v[138:139], v[246:247], v[178:179] op_sel:[0,0,1] op_sel_hi:[1,1,1]
	v_pk_fma_f32 v[238:239], v[112:113], v[244:245], v[238:239]
	v_pk_fma_f32 v[38:39], v[144:145], v[248:249], v[178:179] op_sel:[0,0,1] op_sel_hi:[1,1,1]
	v_pk_fma_f32 v[238:239], v[116:117], v[248:249], v[238:239]
	v_pk_fma_f32 v[32:33], v[146:147], v[250:251], v[178:179] op_sel:[0,0,1] op_sel_hi:[1,1,1]
	v_pk_fma_f32 v[238:239], v[118:119], v[250:251], v[238:239]
	ds_read_b128 v[136:139], v188 offset:21504
	ds_read_b128 v[144:147], v188 offset:21760
	ds_read_b128 v[112:115], v188 offset:4608
	ds_read_b128 v[116:119], v188 offset:4864
	s_waitcnt lgkmcnt(8)
	v_add_f32_e32 v220, v238, v239
	v_pk_fma_f32 v[244:245], v[156:157], v[36:37], v[180:181] op_sel_hi:[1,1,0]
	v_pk_mul_f32 v[240:241], v[130:131], v[48:49]
	v_pk_fma_f32 v[246:247], v[158:159], v[48:49], v[180:181] op_sel_hi:[1,1,0]
	v_pk_fma_f32 v[240:241], v[128:129], v[36:37], v[240:241]
	v_pk_fma_f32 v[248:249], v[168:169], v[38:39], v[180:181] op_sel_hi:[1,1,0]
	v_pk_fma_f32 v[240:241], v[132:133], v[38:39], v[240:241]
	v_pk_fma_f32 v[250:251], v[170:171], v[32:33], v[180:181] op_sel_hi:[1,1,0]
	v_pk_fma_f32 v[240:241], v[134:135], v[32:33], v[240:241]
	ds_read_b128 v[156:159], v188 offset:22016
	ds_read_b128 v[168:171], v188 offset:22272
	ds_read_b128 v[128:131], v188 offset:5120
	ds_read_b128 v[132:135], v188 offset:5376
	s_waitcnt lgkmcnt(8)
	v_add_f32_e32 v221, v240, v241
	v_pk_fma_f32 v[36:37], v[120:121], v[244:245], v[180:181] op_sel:[0,0,1] op_sel_hi:[1,1,1]
	v_pk_mul_f32 v[238:239], v[150:151], v[246:247]
	v_pk_fma_f32 v[48:49], v[122:123], v[246:247], v[180:181] op_sel:[0,0,1] op_sel_hi:[1,1,1]
	v_pk_fma_f32 v[238:239], v[148:149], v[244:245], v[238:239]
	v_pk_fma_f32 v[38:39], v[124:125], v[248:249], v[180:181] op_sel:[0,0,1] op_sel_hi:[1,1,1]
	v_pk_fma_f32 v[238:239], v[152:153], v[248:249], v[238:239]
	v_pk_fma_f32 v[32:33], v[126:127], v[250:251], v[180:181] op_sel:[0,0,1] op_sel_hi:[1,1,1]
	v_pk_fma_f32 v[238:239], v[154:155], v[250:251], v[238:239]
	ds_read_b128 v[120:123], v188 offset:22528
	ds_read_b128 v[124:127], v188 offset:22784
	ds_read_b128 v[148:151], v188 offset:5632
	ds_read_b128 v[152:155], v188 offset:5888
	s_waitcnt lgkmcnt(8)
	v_add_f32_e32 v222, v238, v239
	v_pk_fma_f32 v[244:245], v[136:137], v[36:37], v[182:183] op_sel_hi:[1,1,0]
	v_pk_mul_f32 v[240:241], v[114:115], v[48:49]
	v_pk_fma_f32 v[246:247], v[138:139], v[48:49], v[182:183] op_sel_hi:[1,1,0]
	v_pk_fma_f32 v[240:241], v[112:113], v[36:37], v[240:241]
	v_pk_fma_f32 v[248:249], v[144:145], v[38:39], v[182:183] op_sel_hi:[1,1,0]
	v_pk_fma_f32 v[240:241], v[116:117], v[38:39], v[240:241]
	v_pk_fma_f32 v[250:251], v[146:147], v[32:33], v[182:183] op_sel_hi:[1,1,0]
	v_pk_fma_f32 v[240:241], v[118:119], v[32:33], v[240:241]
	ds_read_b128 v[136:139], v188 offset:23040
	ds_read_b128 v[144:147], v188 offset:23296
	ds_read_b128 v[112:115], v188 offset:6144
	ds_read_b128 v[116:119], v188 offset:6400
	s_waitcnt lgkmcnt(8)
	v_add_f32_e32 v223, v240, v241
	v_pk_fma_f32 v[36:37], v[156:157], v[244:245], v[182:183] op_sel:[0,0,1] op_sel_hi:[1,1,1]
	v_pk_mul_f32 v[238:239], v[130:131], v[246:247]
	v_pk_fma_f32 v[48:49], v[158:159], v[246:247], v[182:183] op_sel:[0,0,1] op_sel_hi:[1,1,1]
	v_pk_fma_f32 v[238:239], v[128:129], v[244:245], v[238:239]
	v_pk_fma_f32 v[38:39], v[168:169], v[248:249], v[182:183] op_sel:[0,0,1] op_sel_hi:[1,1,1]
	v_pk_fma_f32 v[238:239], v[132:133], v[248:249], v[238:239]
	v_pk_fma_f32 v[32:33], v[170:171], v[250:251], v[182:183] op_sel:[0,0,1] op_sel_hi:[1,1,1]
	v_pk_fma_f32 v[238:239], v[134:135], v[250:251], v[238:239]
	ds_read_b128 v[156:159], v188 offset:23552
	ds_read_b128 v[168:171], v188 offset:23808
	ds_read_b128 v[128:131], v188 offset:6656
	ds_read_b128 v[132:135], v188 offset:6912
	s_waitcnt lgkmcnt(8)
; DI float dpp_row_sum16(float v) {
;   v += __int_as_float(__builtin_amdgcn_update_dpp(0, __float_as_int(v), 0xB1, 0xF, 0xF, true));
;   v += __int_as_float(__builtin_amdgcn_update_dpp(0, __float_as_int(v), 0x4E, 0xF, 0xF, true));
;   v += __int_as_float(__builtin_amdgcn_update_dpp(0, __float_as_int(v), 0x141, 0xF, 0xF, true));
;   v += __int_as_float(__builtin_amdgcn_update_dpp(0, __float_as_int(v), 0x140, 0xF, 0xF, true));
;   return v;
; }
	v_add_f32_e32 v224, v238, v239
	v_pk_fma_f32 v[244:245], v[120:121], v[36:37], v[184:185] op_sel_hi:[1,1,0]
	v_pk_mul_f32 v[240:241], v[150:151], v[48:49]
	v_pk_fma_f32 v[246:247], v[122:123], v[48:49], v[184:185] op_sel_hi:[1,1,0]
	v_pk_fma_f32 v[240:241], v[148:149], v[36:37], v[240:241]
	v_pk_fma_f32 v[248:249], v[124:125], v[38:39], v[184:185] op_sel_hi:[1,1,0]
	v_pk_fma_f32 v[240:241], v[152:153], v[38:39], v[240:241]
	v_pk_fma_f32 v[250:251], v[126:127], v[32:33], v[184:185] op_sel_hi:[1,1,0]
	v_pk_fma_f32 v[240:241], v[154:155], v[32:33], v[240:241]
	ds_read_b128 v[120:123], v188 offset:24064
	ds_read_b128 v[124:127], v188 offset:24320
	ds_read_b128 v[148:151], v188 offset:7168
	ds_read_b128 v[152:155], v188 offset:7424
	s_waitcnt lgkmcnt(8)
	v_add_f32_e32 v225, v240, v241
	v_pk_fma_f32 v[36:37], v[136:137], v[244:245], v[184:185] op_sel:[0,0,1] op_sel_hi:[1,1,1]
	v_pk_mul_f32 v[238:239], v[114:115], v[246:247]
	v_pk_fma_f32 v[48:49], v[138:139], v[246:247], v[184:185] op_sel:[0,0,1] op_sel_hi:[1,1,1]
	v_pk_fma_f32 v[238:239], v[112:113], v[244:245], v[238:239]
	v_pk_fma_f32 v[38:39], v[144:145], v[248:249], v[184:185] op_sel:[0,0,1] op_sel_hi:[1,1,1]
	v_pk_fma_f32 v[238:239], v[116:117], v[248:249], v[238:239]
	v_pk_fma_f32 v[32:33], v[146:147], v[250:251], v[184:185] op_sel:[0,0,1] op_sel_hi:[1,1,1]
	v_pk_fma_f32 v[238:239], v[118:119], v[250:251], v[238:239]
	ds_read_b128 v[112:115], v188 offset:7680
	ds_read_b128 v[116:119], v188 offset:7936
	s_waitcnt lgkmcnt(6)
	v_add_f32_e32 v226, v238, v239
	v_pk_fma_f32 v[244:245], v[156:157], v[36:37], v[186:187] op_sel_hi:[1,1,0]
	v_pk_mul_f32 v[240:241], v[130:131], v[48:49]
	v_pk_fma_f32 v[246:247], v[158:159], v[48:49], v[186:187] op_sel_hi:[1,1,0]
	v_pk_fma_f32 v[240:241], v[128:129], v[36:37], v[240:241]
	v_pk_fma_f32 v[248:249], v[168:169], v[38:39], v[186:187] op_sel_hi:[1,1,0]
	v_pk_fma_f32 v[240:241], v[132:133], v[38:39], v[240:241]
	v_pk_fma_f32 v[250:251], v[170:171], v[32:33], v[186:187] op_sel_hi:[1,1,0]
	v_pk_fma_f32 v[240:241], v[134:135], v[32:33], v[240:241]
	s_waitcnt lgkmcnt(2)
	v_add_f32_e32 v227, v240, v241
	v_pk_fma_f32 v[36:37], v[120:121], v[244:245], v[186:187] op_sel:[0,0,1] op_sel_hi:[1,1,1]
	v_pk_mul_f32 v[238:239], v[150:151], v[246:247]
	v_pk_fma_f32 v[48:49], v[122:123], v[246:247], v[186:187] op_sel:[0,0,1] op_sel_hi:[1,1,1]
	v_pk_fma_f32 v[238:239], v[148:149], v[244:245], v[238:239]
	v_pk_fma_f32 v[38:39], v[124:125], v[248:249], v[186:187] op_sel:[0,0,1] op_sel_hi:[1,1,1]
	v_pk_fma_f32 v[238:239], v[152:153], v[248:249], v[238:239]
	v_pk_fma_f32 v[32:33], v[126:127], v[250:251], v[186:187] op_sel:[0,0,1] op_sel_hi:[1,1,1]
	v_pk_fma_f32 v[238:239], v[154:155], v[250:251], v[238:239]
	s_waitcnt lgkmcnt(0)
	v_add_f32_e32 v228, v238, v239
	v_pk_mul_f32 v[240:241], v[114:115], v[48:49]
	v_add_f32_dpp v214, v214, v214 row_mirror row_mask:0xf bank_mask:0x3 bound_ctrl:1
	v_pk_fma_f32 v[240:241], v[112:113], v[36:37], v[240:241]
	v_add_f32_dpp v214, v222, v222 row_mirror row_mask:0xf bank_mask:0xc bound_ctrl:1
	v_pk_fma_f32 v[240:241], v[116:117], v[38:39], v[240:241]
	v_add_f32_dpp v215, v215, v215 row_mirror row_mask:0xf bank_mask:0x3 bound_ctrl:1
	v_pk_fma_f32 v[240:241], v[118:119], v[32:33], v[240:241]
	v_add_f32_dpp v215, v223, v223 row_mirror row_mask:0xf bank_mask:0xc bound_ctrl:1
	v_add_f32_e32 v229, v240, v241
	v_add_f32_dpp v216, v216, v216 row_mirror row_mask:0xf bank_mask:0x3 bound_ctrl:1
	v_add_f32_dpp v216, v224, v224 row_mirror row_mask:0xf bank_mask:0xc bound_ctrl:1
	v_add_f32_dpp v217, v217, v217 row_mirror row_mask:0xf bank_mask:0x3 bound_ctrl:1
	v_add_f32_dpp v217, v225, v225 row_mirror row_mask:0xf bank_mask:0xc bound_ctrl:1
	v_add_f32_dpp v218, v218, v218 row_mirror row_mask:0xf bank_mask:0x3 bound_ctrl:1
	v_add_f32_dpp v218, v226, v226 row_mirror row_mask:0xf bank_mask:0xc bound_ctrl:1
	v_add_f32_dpp v219, v219, v219 row_mirror row_mask:0xf bank_mask:0x3 bound_ctrl:1
	v_add_f32_dpp v219, v227, v227 row_mirror row_mask:0xf bank_mask:0xc bound_ctrl:1
	v_add_f32_dpp v220, v220, v220 row_mirror row_mask:0xf bank_mask:0x3 bound_ctrl:1
	v_add_f32_dpp v220, v228, v228 row_mirror row_mask:0xf bank_mask:0xc bound_ctrl:1
	v_add_f32_dpp v221, v221, v221 row_mirror row_mask:0xf bank_mask:0x3 bound_ctrl:1
	v_add_f32_dpp v221, v229, v229 row_mirror row_mask:0xf bank_mask:0xc bound_ctrl:1
	v_add_f32_dpp v214, v214, v214 row_half_mirror row_mask:0xf bank_mask:0x5 bound_ctrl:1
	v_add_f32_dpp v214, v218, v218 row_half_mirror row_mask:0xf bank_mask:0xa bound_ctrl:1
	v_add_f32_dpp v215, v215, v215 row_half_mirror row_mask:0xf bank_mask:0x5 bound_ctrl:1
	v_add_f32_dpp v215, v219, v219 row_half_mirror row_mask:0xf bank_mask:0xa bound_ctrl:1
	v_add_f32_dpp v216, v216, v216 row_half_mirror row_mask:0xf bank_mask:0x5 bound_ctrl:1
	v_add_f32_dpp v216, v220, v220 row_half_mirror row_mask:0xf bank_mask:0xa bound_ctrl:1
	v_add_f32_dpp v217, v217, v217 row_half_mirror row_mask:0xf bank_mask:0x5 bound_ctrl:1
	v_add_f32_dpp v217, v221, v221 row_half_mirror row_mask:0xf bank_mask:0xa bound_ctrl:1
	v_add_f32_dpp v192, v214, v214 quad_perm:[2,3,0,1] row_mask:0xf bank_mask:0xf bound_ctrl:1
	v_add_f32_dpp v193, v216, v216 quad_perm:[2,3,0,1] row_mask:0xf bank_mask:0xf bound_ctrl:1
	v_add_f32_dpp v194, v215, v215 quad_perm:[2,3,0,1] row_mask:0xf bank_mask:0xf bound_ctrl:1
	v_add_f32_dpp v195, v217, v217 quad_perm:[2,3,0,1] row_mask:0xf bank_mask:0xf bound_ctrl:1
	v_cndmask_b32_e64 v214, v193, v192, s[42:43]
	v_cndmask_b32_e64 v215, v195, v194, s[42:43]
	s_nop 0
	v_add_f32_dpp v192, v214, v214 quad_perm:[1,0,3,2] row_mask:0xf bank_mask:0xf bound_ctrl:1
	v_add_f32_dpp v193, v215, v215 quad_perm:[1,0,3,2] row_mask:0xf bank_mask:0xf bound_ctrl:1
	v_or_b32_e32 v24, s25, v26
	s_and_b64 vcc, exec, s[0:1]
	v_cndmask_b32_e64 v25, v193, v192, s[44:45]
	v_cndmask_b32_e64 v160, v160, 0, s[72:73]
	v_fmac_f32_e32 v25, v160, v161
	s_cbranch_vccz .LBB0_218
	s_mov_b64 s[36:37], -1
	s_and_b64 vcc, exec, s[76:77]
	s_cbranch_vccz .LBB0_222
	v_sub_u32_e32 v91, 0x21ff, v24
	s_mov_b64 s[36:37], 0

.LBB0_224:
	s_waitcnt vmcnt(4)
	v_lshlrev_b32_e32 v28, 16, v8
	v_and_b32_e32 v29, 0xffff0000, v8
	v_lshlrev_b32_e32 v30, 16, v9
	v_and_b32_e32 v31, 0xffff0000, v9
	v_lshlrev_b32_e32 v8, 16, v10
	v_and_b32_e32 v9, 0xffff0000, v10
	v_lshlrev_b32_e32 v10, 16, v11
	v_and_b32_e32 v11, 0xffff0000, v11
	ds_write_b128 v64, v[28:31] offset:36864
	ds_write_b128 v64, v[8:11] offset:37120
	v_add_f32_e32 v165, v28, v29
	v_add_f32_e32 v165, v165, v30
	v_add_f32_e32 v165, v165, v31
	v_add_f32_e32 v165, v165, v8
	v_add_f32_e32 v165, v165, v9
	v_add_f32_e32 v165, v165, v10
	v_add_f32_e32 v165, v165, v11
	s_nop 1
	v_add_f32_dpp v165, v165, v165 quad_perm:[1,0,3,2] row_mask:0xf bank_mask:0xf bound_ctrl:1
	s_nop 1
	v_add_f32_dpp v165, v165, v165 quad_perm:[2,3,0,1] row_mask:0xf bank_mask:0xf bound_ctrl:1
	s_nop 1
	v_add_f32_dpp v165, v165, v165 row_half_mirror row_mask:0xf bank_mask:0xf bound_ctrl:1
	s_nop 1
	v_add_f32_dpp v165, v165, v165 row_mirror row_mask:0xf bank_mask:0xf bound_ctrl:1
	ds_write_b32 v164, v165 offset:128
	s_waitcnt vmcnt(3)
	v_lshlrev_b32_e32 v8, 16, v4
	v_and_b32_e32 v9, 0xffff0000, v4
	v_lshlrev_b32_e32 v10, 16, v5
	v_and_b32_e32 v11, 0xffff0000, v5
	v_lshlrev_b32_e32 v4, 16, v6
	v_and_b32_e32 v5, 0xffff0000, v6
	v_lshlrev_b32_e32 v6, 16, v7
	v_and_b32_e32 v7, 0xffff0000, v7
	v_sub_f32_e32 v8, 1.0, v8
	v_sub_f32_e32 v9, 1.0, v9
	v_sub_f32_e32 v10, 1.0, v10
	v_sub_f32_e32 v11, 1.0, v11
	ds_write_b128 v64, v[8:11] offset:53248
	v_sub_f32_e32 v4, 1.0, v4
	v_sub_f32_e32 v5, 1.0, v5
	v_sub_f32_e32 v6, 1.0, v6
	v_sub_f32_e32 v7, 1.0, v7
	ds_write_b128 v64, v[4:7] offset:53504
	s_and_saveexec_b64 s[30:31], s[38:39]
	s_cbranch_execz .LBB0_226
	v_lshlrev_b32_e32 v4, 16, v0
	v_and_b32_e32 v5, 0xffff0000, v0
	v_lshlrev_b32_e32 v6, 16, v1
	v_and_b32_e32 v7, 0xffff0000, v1
	v_lshlrev_b32_e32 v8, 16, v2
	v_and_b32_e32 v9, 0xffff0000, v2
	v_lshlrev_b32_e32 v10, 16, v3
	v_and_b32_e32 v11, 0xffff0000, v3
	ds_write_b128 v73, v[4:7]
	ds_write_b128 v73, v[8:11] offset:16

.LBB0_243:
	v_lshl_add_u32 v188, s30, 9, v69
	v_lshl_add_u32 v189, s30, 7, v72
	v_add_u32_e32 v190, 0x11400, v189
	v_add_u32_e32 v189, 0x11000, v189
	v_add_u32_e32 v160, v189, v142
	v_lshl_add_u32 v161, s30, 2, v143
	ds_read2_b32 v[172:173], v189 offset1:32
	ds_read2_b32 v[174:175], v189 offset0:64 offset1:96
	ds_read2_b32 v[176:177], v189 offset0:128 offset1:160
	ds_read2_b32 v[178:179], v189 offset0:192 offset1:224
	ds_read2_b32 v[180:181], v190 offset1:32
	ds_read2_b32 v[182:183], v190 offset0:64 offset1:96
	ds_read2_b32 v[184:185], v190 offset0:128 offset1:160
	ds_read2_b32 v[186:187], v190 offset0:192 offset1:224
	ds_read_b32 v160, v160
	ds_read_b32 v161, v161 offset:128
	ds_read_b128 v[120:123], v188 offset:53248
	ds_read_b128 v[124:127], v188 offset:53504
	ds_read_b128 v[112:115], v188 offset:36864
	ds_read_b128 v[116:119], v188 offset:37120
	ds_read_b128 v[136:139], v188 offset:53760
	ds_read_b128 v[144:147], v188 offset:54016
	ds_read_b128 v[156:159], v188 offset:54272
	ds_read_b128 v[168:171], v188 offset:54528
	ds_read_b128 v[128:131], v188 offset:37376
	ds_read_b128 v[132:135], v188 offset:37632
	s_waitcnt lgkmcnt(8)
	v_pk_add_f32 v[36:37], v[36:37], v[172:173] op_sel_hi:[1,0] neg_lo:[0,1] neg_hi:[0,1]
	v_pk_add_f32 v[48:49], v[48:49], v[172:173] op_sel_hi:[1,0] neg_lo:[0,1] neg_hi:[0,1]
	v_pk_add_f32 v[38:39], v[38:39], v[172:173] op_sel_hi:[1,0] neg_lo:[0,1] neg_hi:[0,1]
	v_pk_add_f32 v[32:33], v[32:33], v[172:173] op_sel_hi:[1,0] neg_lo:[0,1] neg_hi:[0,1]
	v_sub_f32_e32 v172, v172, v173
	v_sub_f32_e32 v173, v173, v174
	v_sub_f32_e32 v174, v174, v175
	v_sub_f32_e32 v175, v175, v176
	v_sub_f32_e32 v176, v176, v177
	v_sub_f32_e32 v177, v177, v178
	v_sub_f32_e32 v178, v178, v179
	v_sub_f32_e32 v179, v179, v180
	v_sub_f32_e32 v180, v180, v181
	v_sub_f32_e32 v181, v181, v182
	v_sub_f32_e32 v182, v182, v183
	v_sub_f32_e32 v183, v183, v184
	v_sub_f32_e32 v184, v184, v185
	v_sub_f32_e32 v185, v185, v186
	v_sub_f32_e32 v186, v186, v187
	v_pk_fma_f32 v[244:245], v[120:121], v[36:37], v[172:173] op_sel_hi:[1,1,0]
	v_pk_fma_f32 v[246:247], v[122:123], v[48:49], v[172:173] op_sel_hi:[1,1,0]
	v_pk_fma_f32 v[248:249], v[124:125], v[38:39], v[172:173] op_sel_hi:[1,1,0]
	v_pk_fma_f32 v[250:251], v[126:127], v[32:33], v[172:173] op_sel_hi:[1,1,0]
	ds_read_b128 v[120:123], v188 offset:54784
	ds_read_b128 v[124:127], v188 offset:55040
	ds_read_b128 v[148:151], v188 offset:37888
	ds_read_b128 v[152:155], v188 offset:38144
	s_waitcnt lgkmcnt(8)
	v_pk_fma_f32 v[36:37], v[136:137], v[244:245], v[172:173] op_sel:[0,0,1] op_sel_hi:[1,1,1]
	v_pk_mul_f32 v[238:239], v[114:115], v[246:247]
	v_pk_fma_f32 v[48:49], v[138:139], v[246:247], v[172:173] op_sel:[0,0,1] op_sel_hi:[1,1,1]
	v_pk_fma_f32 v[238:239], v[112:113], v[244:245], v[238:239]
	v_pk_fma_f32 v[38:39], v[144:145], v[248:249], v[172:173] op_sel:[0,0,1] op_sel_hi:[1,1,1]
	v_pk_fma_f32 v[238:239], v[116:117], v[248:249], v[238:239]
	v_pk_fma_f32 v[32:33], v[146:147], v[250:251], v[172:173] op_sel:[0,0,1] op_sel_hi:[1,1,1]
	v_pk_fma_f32 v[238:239], v[118:119], v[250:251], v[238:239]
	ds_read_b128 v[136:139], v188 offset:55296
	ds_read_b128 v[144:147], v188 offset:55552
	ds_read_b128 v[112:115], v188 offset:38400
	ds_read_b128 v[116:119], v188 offset:38656
	s_waitcnt lgkmcnt(8)
	v_add_f32_e32 v214, v238, v239
	v_pk_fma_f32 v[244:245], v[156:157], v[36:37], v[174:175] op_sel_hi:[1,1,0]
	v_pk_mul_f32 v[240:241], v[130:131], v[48:49]
	v_pk_fma_f32 v[246:247], v[158:159], v[48:49], v[174:175] op_sel_hi:[1,1,0]
	v_pk_fma_f32 v[240:241], v[128:129], v[36:37], v[240:241]
	v_pk_fma_f32 v[248:249], v[168:169], v[38:39], v[174:175] op_sel_hi:[1,1,0]
	v_pk_fma_f32 v[240:241], v[132:133], v[38:39], v[240:241]
	v_pk_fma_f32 v[250:251], v[170:171], v[32:33], v[174:175] op_sel_hi:[1,1,0]
	v_pk_fma_f32 v[240:241], v[134:135], v[32:33], v[240:241]
	ds_read_b128 v[156:159], v188 offset:55808
	ds_read_b128 v[168:171], v188 offset:56064
	ds_read_b128 v[128:131], v188 offset:38912
	ds_read_b128 v[132:135], v188 offset:39168
	s_waitcnt lgkmcnt(8)
	v_add_f32_e32 v215, v240, v241
	v_pk_fma_f32 v[36:37], v[120:121], v[244:245], v[174:175] op_sel:[0,0,1] op_sel_hi:[1,1,1]
	v_pk_mul_f32 v[238:239], v[150:151], v[246:247]
	v_pk_fma_f32 v[48:49], v[122:123], v[246:247], v[174:175] op_sel:[0,0,1] op_sel_hi:[1,1,1]
	v_pk_fma_f32 v[238:239], v[148:149], v[244:245], v[238:239]
	v_pk_fma_f32 v[38:39], v[124:125], v[248:249], v[174:175] op_sel:[0,0,1] op_sel_hi:[1,1,1]
	v_pk_fma_f32 v[238:239], v[152:153], v[248:249], v[238:239]
	v_pk_fma_f32 v[32:33], v[126:127], v[250:251], v[174:175] op_sel:[0,0,1] op_sel_hi:[1,1,1]
	v_pk_fma_f32 v[238:239], v[154:155], v[250:251], v[238:239]
	ds_read_b128 v[120:123], v188 offset:56320
	ds_read_b128 v[124:127], v188 offset:56576
	ds_read_b128 v[148:151], v188 offset:39424
	ds_read_b128 v[152:155], v188 offset:39680
	s_waitcnt lgkmcnt(8)
	v_add_f32_e32 v216, v238, v239
	v_pk_fma_f32 v[244:245], v[136:137], v[36:37], v[176:177] op_sel_hi:[1,1,0]
	v_pk_mul_f32 v[240:241], v[114:115], v[48:49]
	v_pk_fma_f32 v[246:247], v[138:139], v[48:49], v[176:177] op_sel_hi:[1,1,0]
	v_pk_fma_f32 v[240:241], v[112:113], v[36:37], v[240:241]
	v_pk_fma_f32 v[248:249], v[144:145], v[38:39], v[176:177] op_sel_hi:[1,1,0]
	v_pk_fma_f32 v[240:241], v[116:117], v[38:39], v[240:241]
	v_pk_fma_f32 v[250:251], v[146:147], v[32:33], v[176:177] op_sel_hi:[1,1,0]
	v_pk_fma_f32 v[240:241], v[118:119], v[32:33], v[240:241]
	ds_read_b128 v[136:139], v188 offset:56832
	ds_read_b128 v[144:147], v188 offset:57088
	ds_read_b128 v[112:115], v188 offset:39936
	ds_read_b128 v[116:119], v188 offset:40192
	s_waitcnt lgkmcnt(8)
	v_add_f32_e32 v217, v240, v241
	v_pk_fma_f32 v[36:37], v[156:157], v[244:245], v[176:177] op_sel:[0,0,1] op_sel_hi:[1,1,1]
	v_pk_mul_f32 v[238:239], v[130:131], v[246:247]
	v_pk_fma_f32 v[48:49], v[158:159], v[246:247], v[176:177] op_sel:[0,0,1] op_sel_hi:[1,1,1]
	v_pk_fma_f32 v[238:239], v[128:129], v[244:245], v[238:239]
	v_pk_fma_f32 v[38:39], v[168:169], v[248:249], v[176:177] op_sel:[0,0,1] op_sel_hi:[1,1,1]
	v_pk_fma_f32 v[238:239], v[132:133], v[248:249], v[238:239]
	v_pk_fma_f32 v[32:33], v[170:171], v[250:251], v[176:177] op_sel:[0,0,1] op_sel_hi:[1,1,1]
	v_pk_fma_f32 v[238:239], v[134:135], v[250:251], v[238:239]
	ds_read_b128 v[156:159], v188 offset:57344
	ds_read_b128 v[168:171], v188 offset:57600
	ds_read_b128 v[128:131], v188 offset:40448
	ds_read_b128 v[132:135], v188 offset:40704
	s_waitcnt lgkmcnt(8)
	v_add_f32_e32 v218, v238, v239
	v_pk_fma_f32 v[244:245], v[120:121], v[36:37], v[178:179] op_sel_hi:[1,1,0]
	v_pk_mul_f32 v[240:241], v[150:151], v[48:49]
	v_pk_fma_f32 v[246:247], v[122:123], v[48:49], v[178:179] op_sel_hi:[1,1,0]
	v_pk_fma_f32 v[240:241], v[148:149], v[36:37], v[240:241]
	v_pk_fma_f32 v[248:249], v[124:125], v[38:39], v[178:179] op_sel_hi:[1,1,0]
	v_pk_fma_f32 v[240:241], v[152:153], v[38:39], v[240:241]
	v_pk_fma_f32 v[250:251], v[126:127], v[32:33], v[178:179] op_sel_hi:[1,1,0]
	v_pk_fma_f32 v[240:241], v[154:155], v[32:33], v[240:241]
	ds_read_b128 v[120:123], v188 offset:57856
	ds_read_b128 v[124:127], v188 offset:58112
	ds_read_b128 v[148:151], v188 offset:40960
	ds_read_b128 v[152:155], v188 offset:41216
	s_waitcnt lgkmcnt(8)
	v_add_f32_e32 v219, v240, v241
	v_pk_fma_f32 v[36:37], v[136:137], v[244:245], v[178:179] op_sel:[0,0,1] op_sel_hi:[1,1,1]
	v_pk_mul_f32 v[238:239], v[114:115], v[246:247]
	v_pk_fma_f32 v[48:49], v[138:139], v[246:247], v[178:179] op_sel:[0,0,1] op_sel_hi:[1,1,1]
	v_pk_fma_f32 v[238:239], v[112:113], v[244:245], v[238:239]
	v_pk_fma_f32 v[38:39], v[144:145], v[248:249], v[178:179] op_sel:[0,0,1] op_sel_hi:[1,1,1]
	v_pk_fma_f32 v[238:239], v[116:117], v[248:249], v[238:239]
	v_pk_fma_f32 v[32:33], v[146:147], v[250:251], v[178:179] op_sel:[0,0,1] op_sel_hi:[1,1,1]
	v_pk_fma_f32 v[238:239], v[118:119], v[250:251], v[238:239]
	ds_read_b128 v[136:139], v188 offset:58368
	ds_read_b128 v[144:147], v188 offset:58624
	ds_read_b128 v[112:115], v188 offset:41472
	ds_read_b128 v[116:119], v188 offset:41728
	s_waitcnt lgkmcnt(8)
	v_add_f32_e32 v220, v238, v239
	v_pk_fma_f32 v[244:245], v[156:157], v[36:37], v[180:181] op_sel_hi:[1,1,0]
	v_pk_mul_f32 v[240:241], v[130:131], v[48:49]
	v_pk_fma_f32 v[246:247], v[158:159], v[48:49], v[180:181] op_sel_hi:[1,1,0]
	v_pk_fma_f32 v[240:241], v[128:129], v[36:37], v[240:241]
	v_pk_fma_f32 v[248:249], v[168:169], v[38:39], v[180:181] op_sel_hi:[1,1,0]
	v_pk_fma_f32 v[240:241], v[132:133], v[38:39], v[240:241]
	v_pk_fma_f32 v[250:251], v[170:171], v[32:33], v[180:181] op_sel_hi:[1,1,0]
	v_pk_fma_f32 v[240:241], v[134:135], v[32:33], v[240:241]
	ds_read_b128 v[156:159], v188 offset:58880
	ds_read_b128 v[168:171], v188 offset:59136
	ds_read_b128 v[128:131], v188 offset:41984
	ds_read_b128 v[132:135], v188 offset:42240
	s_waitcnt lgkmcnt(8)
	v_add_f32_e32 v221, v240, v241
	v_pk_fma_f32 v[36:37], v[120:121], v[244:245], v[180:181] op_sel:[0,0,1] op_sel_hi:[1,1,1]
	v_pk_mul_f32 v[238:239], v[150:151], v[246:247]
	v_pk_fma_f32 v[48:49], v[122:123], v[246:247], v[180:181] op_sel:[0,0,1] op_sel_hi:[1,1,1]
	v_pk_fma_f32 v[238:239], v[148:149], v[244:245], v[238:239]
	v_pk_fma_f32 v[38:39], v[124:125], v[248:249], v[180:181] op_sel:[0,0,1] op_sel_hi:[1,1,1]
	v_pk_fma_f32 v[238:239], v[152:153], v[248:249], v[238:239]
	v_pk_fma_f32 v[32:33], v[126:127], v[250:251], v[180:181] op_sel:[0,0,1] op_sel_hi:[1,1,1]
	v_pk_fma_f32 v[238:239], v[154:155], v[250:251], v[238:239]
	ds_read_b128 v[120:123], v188 offset:59392
	ds_read_b128 v[124:127], v188 offset:59648
	ds_read_b128 v[148:151], v188 offset:42496
	ds_read_b128 v[152:155], v188 offset:42752
	s_waitcnt lgkmcnt(8)
	v_add_f32_e32 v222, v238, v239
	v_pk_fma_f32 v[244:245], v[136:137], v[36:37], v[182:183] op_sel_hi:[1,1,0]
	v_pk_mul_f32 v[240:241], v[114:115], v[48:49]
	v_pk_fma_f32 v[246:247], v[138:139], v[48:49], v[182:183] op_sel_hi:[1,1,0]
	v_pk_fma_f32 v[240:241], v[112:113], v[36:37], v[240:241]
	v_pk_fma_f32 v[248:249], v[144:145], v[38:39], v[182:183] op_sel_hi:[1,1,0]
	v_pk_fma_f32 v[240:241], v[116:117], v[38:39], v[240:241]
	v_pk_fma_f32 v[250:251], v[146:147], v[32:33], v[182:183] op_sel_hi:[1,1,0]
	v_pk_fma_f32 v[240:241], v[118:119], v[32:33], v[240:241]
	ds_read_b128 v[136:139], v188 offset:59904
	ds_read_b128 v[144:147], v188 offset:60160
	ds_read_b128 v[112:115], v188 offset:43008
	ds_read_b128 v[116:119], v188 offset:43264
	s_waitcnt lgkmcnt(8)
	v_add_f32_e32 v223, v240, v241
	v_pk_fma_f32 v[36:37], v[156:157], v[244:245], v[182:183] op_sel:[0,0,1] op_sel_hi:[1,1,1]
	v_pk_mul_f32 v[238:239], v[130:131], v[246:247]
	v_pk_fma_f32 v[48:49], v[158:159], v[246:247], v[182:183] op_sel:[0,0,1] op_sel_hi:[1,1,1]
	v_pk_fma_f32 v[238:239], v[128:129], v[244:245], v[238:239]
	v_pk_fma_f32 v[38:39], v[168:169], v[248:249], v[182:183] op_sel:[0,0,1] op_sel_hi:[1,1,1]
	v_pk_fma_f32 v[238:239], v[132:133], v[248:249], v[238:239]
	v_pk_fma_f32 v[32:33], v[170:171], v[250:251], v[182:183] op_sel:[0,0,1] op_sel_hi:[1,1,1]
	v_pk_fma_f32 v[238:239], v[134:135], v[250:251], v[238:239]
	ds_read_b128 v[156:159], v188 offset:60416
	ds_read_b128 v[168:171], v188 offset:60672
	ds_read_b128 v[128:131], v188 offset:43520
	ds_read_b128 v[132:135], v188 offset:43776
	s_waitcnt lgkmcnt(8)
	v_add_f32_e32 v224, v238, v239
	v_pk_fma_f32 v[244:245], v[120:121], v[36:37], v[184:185] op_sel_hi:[1,1,0]
	v_pk_mul_f32 v[240:241], v[150:151], v[48:49]
	v_pk_fma_f32 v[246:247], v[122:123], v[48:49], v[184:185] op_sel_hi:[1,1,0]
	v_pk_fma_f32 v[240:241], v[148:149], v[36:37], v[240:241]
	v_pk_fma_f32 v[248:249], v[124:125], v[38:39], v[184:185] op_sel_hi:[1,1,0]
	v_pk_fma_f32 v[240:241], v[152:153], v[38:39], v[240:241]
	v_pk_fma_f32 v[250:251], v[126:127], v[32:33], v[184:185] op_sel_hi:[1,1,0]
	v_pk_fma_f32 v[240:241], v[154:155], v[32:33], v[240:241]
	ds_read_b128 v[120:123], v188 offset:60928
	ds_read_b128 v[124:127], v188 offset:61184
	ds_read_b128 v[148:151], v188 offset:44032
	ds_read_b128 v[152:155], v188 offset:44288
	s_waitcnt lgkmcnt(8)
	v_add_f32_e32 v225, v240, v241
	v_pk_fma_f32 v[36:37], v[136:137], v[244:245], v[184:185] op_sel:[0,0,1] op_sel_hi:[1,1,1]
	v_pk_mul_f32 v[238:239], v[114:115], v[246:247]
	v_pk_fma_f32 v[48:49], v[138:139], v[246:247], v[184:185] op_sel:[0,0,1] op_sel_hi:[1,1,1]
	v_pk_fma_f32 v[238:239], v[112:113], v[244:245], v[238:239]
	v_pk_fma_f32 v[38:39], v[144:145], v[248:249], v[184:185] op_sel:[0,0,1] op_sel_hi:[1,1,1]
	v_pk_fma_f32 v[238:239], v[116:117], v[248:249], v[238:239]
	v_pk_fma_f32 v[32:33], v[146:147], v[250:251], v[184:185] op_sel:[0,0,1] op_sel_hi:[1,1,1]
	v_pk_fma_f32 v[238:239], v[118:119], v[250:251], v[238:239]
	ds_read_b128 v[112:115], v188 offset:44544
	ds_read_b128 v[116:119], v188 offset:44800
	s_waitcnt lgkmcnt(6)
	v_add_f32_e32 v226, v238, v239
	v_pk_fma_f32 v[244:245], v[156:157], v[36:37], v[186:187] op_sel_hi:[1,1,0]
	v_pk_mul_f32 v[240:241], v[130:131], v[48:49]
	v_pk_fma_f32 v[246:247], v[158:159], v[48:49], v[186:187] op_sel_hi:[1,1,0]
	v_pk_fma_f32 v[240:241], v[128:129], v[36:37], v[240:241]
	v_pk_fma_f32 v[248:249], v[168:169], v[38:39], v[186:187] op_sel_hi:[1,1,0]
	v_pk_fma_f32 v[240:241], v[132:133], v[38:39], v[240:241]
	v_pk_fma_f32 v[250:251], v[170:171], v[32:33], v[186:187] op_sel_hi:[1,1,0]
	v_pk_fma_f32 v[240:241], v[134:135], v[32:33], v[240:241]
	s_waitcnt lgkmcnt(2)
	v_add_f32_e32 v227, v240, v241
	v_pk_fma_f32 v[36:37], v[120:121], v[244:245], v[186:187] op_sel:[0,0,1] op_sel_hi:[1,1,1]
	v_pk_mul_f32 v[238:239], v[150:151], v[246:247]
	v_pk_fma_f32 v[48:49], v[122:123], v[246:247], v[186:187] op_sel:[0,0,1] op_sel_hi:[1,1,1]
	v_pk_fma_f32 v[238:239], v[148:149], v[244:245], v[238:239]
	v_pk_fma_f32 v[38:39], v[124:125], v[248:249], v[186:187] op_sel:[0,0,1] op_sel_hi:[1,1,1]
	v_pk_fma_f32 v[238:239], v[152:153], v[248:249], v[238:239]
	v_pk_fma_f32 v[32:33], v[126:127], v[250:251], v[186:187] op_sel:[0,0,1] op_sel_hi:[1,1,1]
	v_pk_fma_f32 v[238:239], v[154:155], v[250:251], v[238:239]
	s_waitcnt lgkmcnt(0)
	v_add_f32_e32 v228, v238, v239
	v_pk_mul_f32 v[240:241], v[114:115], v[48:49]
	v_add_f32_dpp v214, v214, v214 row_mirror row_mask:0xf bank_mask:0x3 bound_ctrl:1
	v_pk_fma_f32 v[240:241], v[112:113], v[36:37], v[240:241]
	v_add_f32_dpp v214, v222, v222 row_mirror row_mask:0xf bank_mask:0xc bound_ctrl:1
	v_pk_fma_f32 v[240:241], v[116:117], v[38:39], v[240:241]
	v_add_f32_dpp v215, v215, v215 row_mirror row_mask:0xf bank_mask:0x3 bound_ctrl:1
	v_pk_fma_f32 v[240:241], v[118:119], v[32:33], v[240:241]
	v_add_f32_dpp v215, v223, v223 row_mirror row_mask:0xf bank_mask:0xc bound_ctrl:1
	v_add_f32_e32 v229, v240, v241
	v_add_f32_dpp v216, v216, v216 row_mirror row_mask:0xf bank_mask:0x3 bound_ctrl:1
	v_add_f32_dpp v216, v224, v224 row_mirror row_mask:0xf bank_mask:0xc bound_ctrl:1
	v_add_f32_dpp v217, v217, v217 row_mirror row_mask:0xf bank_mask:0x3 bound_ctrl:1
	v_add_f32_dpp v217, v225, v225 row_mirror row_mask:0xf bank_mask:0xc bound_ctrl:1
	v_add_f32_dpp v218, v218, v218 row_mirror row_mask:0xf bank_mask:0x3 bound_ctrl:1
	v_add_f32_dpp v218, v226, v226 row_mirror row_mask:0xf bank_mask:0xc bound_ctrl:1
	v_add_f32_dpp v219, v219, v219 row_mirror row_mask:0xf bank_mask:0x3 bound_ctrl:1
	v_add_f32_dpp v219, v227, v227 row_mirror row_mask:0xf bank_mask:0xc bound_ctrl:1
	v_add_f32_dpp v220, v220, v220 row_mirror row_mask:0xf bank_mask:0x3 bound_ctrl:1
	v_add_f32_dpp v220, v228, v228 row_mirror row_mask:0xf bank_mask:0xc bound_ctrl:1
	v_add_f32_dpp v221, v221, v221 row_mirror row_mask:0xf bank_mask:0x3 bound_ctrl:1
	v_add_f32_dpp v221, v229, v229 row_mirror row_mask:0xf bank_mask:0xc bound_ctrl:1
	v_add_f32_dpp v214, v214, v214 row_half_mirror row_mask:0xf bank_mask:0x5 bound_ctrl:1
	v_add_f32_dpp v214, v218, v218 row_half_mirror row_mask:0xf bank_mask:0xa bound_ctrl:1
	v_add_f32_dpp v215, v215, v215 row_half_mirror row_mask:0xf bank_mask:0x5 bound_ctrl:1
	v_add_f32_dpp v215, v219, v219 row_half_mirror row_mask:0xf bank_mask:0xa bound_ctrl:1
	v_add_f32_dpp v216, v216, v216 row_half_mirror row_mask:0xf bank_mask:0x5 bound_ctrl:1
	v_add_f32_dpp v216, v220, v220 row_half_mirror row_mask:0xf bank_mask:0xa bound_ctrl:1
	v_add_f32_dpp v217, v217, v217 row_half_mirror row_mask:0xf bank_mask:0x5 bound_ctrl:1
	v_add_f32_dpp v217, v221, v221 row_half_mirror row_mask:0xf bank_mask:0xa bound_ctrl:1
	v_add_f32_dpp v192, v214, v214 quad_perm:[2,3,0,1] row_mask:0xf bank_mask:0xf bound_ctrl:1
	v_add_f32_dpp v193, v216, v216 quad_perm:[2,3,0,1] row_mask:0xf bank_mask:0xf bound_ctrl:1
	v_add_f32_dpp v194, v215, v215 quad_perm:[2,3,0,1] row_mask:0xf bank_mask:0xf bound_ctrl:1
	v_add_f32_dpp v195, v217, v217 quad_perm:[2,3,0,1] row_mask:0xf bank_mask:0xf bound_ctrl:1
	v_cndmask_b32_e64 v214, v193, v192, s[42:43]
	v_cndmask_b32_e64 v215, v195, v194, s[42:43]
	s_nop 0
	v_add_f32_dpp v192, v214, v214 quad_perm:[1,0,3,2] row_mask:0xf bank_mask:0xf bound_ctrl:1
	v_add_f32_dpp v193, v215, v215 quad_perm:[1,0,3,2] row_mask:0xf bank_mask:0xf bound_ctrl:1
	v_or_b32_e32 v24, s30, v74
	s_and_b64 vcc, exec, s[0:1]
	v_cndmask_b32_e64 v25, v193, v192, s[44:45]
	v_cndmask_b32_e64 v160, v160, 0, s[72:73]
	v_fmac_f32_e32 v25, v160, v161
	s_cbranch_vccz .LBB0_242
	s_mov_b64 s[30:31], -1
	s_and_b64 vcc, exec, s[76:77]
	s_cbranch_vccz .LBB0_246
	v_sub_u32_e32 v27, 0x21ff, v24
	s_mov_b64 s[30:31], 0

.LBB0_248:
	s_waitcnt vmcnt(5)
	v_lshlrev_b32_e32 v26, 16, v21
	v_lshlrev_b32_e32 v24, 16, v20
	v_lshlrev_b32_e32 v30, 16, v23
	v_lshlrev_b32_e32 v28, 16, v22
	v_and_b32_e32 v27, 0xffff0000, v21
	v_and_b32_e32 v25, 0xffff0000, v20
	v_and_b32_e32 v31, 0xffff0000, v23
	v_and_b32_e32 v29, 0xffff0000, v22
	ds_write_b128 v64, v[28:31] offset:256
	ds_write_b128 v64, v[24:27]
	v_add_f32_e32 v165, v28, v29
	v_add_f32_e32 v165, v165, v30
	v_add_f32_e32 v165, v165, v31
	v_add_f32_e32 v165, v165, v24
	v_add_f32_e32 v165, v165, v25
	v_add_f32_e32 v165, v165, v26
	v_add_f32_e32 v165, v165, v27
	s_nop 1
	v_add_f32_dpp v165, v165, v165 quad_perm:[1,0,3,2] row_mask:0xf bank_mask:0xf bound_ctrl:1
	s_nop 1
	v_add_f32_dpp v165, v165, v165 quad_perm:[2,3,0,1] row_mask:0xf bank_mask:0xf bound_ctrl:1
	s_nop 1
	v_add_f32_dpp v165, v165, v165 row_half_mirror row_mask:0xf bank_mask:0xf bound_ctrl:1
	s_nop 1
	v_add_f32_dpp v165, v165, v165 row_mirror row_mask:0xf bank_mask:0xf bound_ctrl:1
	ds_write_b32 v164, v165
	s_waitcnt vmcnt(4)
	v_lshlrev_b32_e32 v26, 16, v19
	v_lshlrev_b32_e32 v24, 16, v18
	v_and_b32_e32 v27, 0xffff0000, v19
	v_and_b32_e32 v25, 0xffff0000, v18
	v_lshlrev_b32_e32 v22, 16, v17
	v_lshlrev_b32_e32 v20, 16, v16
	v_and_b32_e32 v23, 0xffff0000, v17
	v_and_b32_e32 v21, 0xffff0000, v16
	v_sub_f32_e32 v24, 1.0, v24
	v_sub_f32_e32 v25, 1.0, v25
	v_sub_f32_e32 v26, 1.0, v26
	v_sub_f32_e32 v27, 1.0, v27
	ds_write_b128 v64, v[24:27] offset:16640
	v_sub_f32_e32 v20, 1.0, v20
	v_sub_f32_e32 v21, 1.0, v21
	v_sub_f32_e32 v22, 1.0, v22
	v_sub_f32_e32 v23, 1.0, v23
	ds_write_b128 v64, v[20:23] offset:16384
	s_and_saveexec_b64 s[30:31], s[38:39]
	s_cbranch_execz .LBB0_201
	v_lshlrev_b32_e32 v16, 16, v12
	v_and_b32_e32 v17, 0xffff0000, v12
	v_lshlrev_b32_e32 v18, 16, v13
	v_and_b32_e32 v19, 0xffff0000, v13
	v_lshlrev_b32_e32 v20, 16, v14
	v_and_b32_e32 v21, 0xffff0000, v14
	v_lshlrev_b32_e32 v22, 16, v15
	v_and_b32_e32 v23, 0xffff0000, v15
	ds_write_b128 v65, v[16:19] offset:32768
	ds_write_b128 v65, v[20:23] offset:32784
	s_branch .LBB0_201
